# MLP2 regrouped: 4 same-XCD workgroups walk the same 4 row panels (own column tile) so the HID A-operand is fetched once per group and shared through L2; two 4-WG barriers
# speedup vs baseline: 1.0396x; 1.0396x over previous
; #define PG8_STAGE(bufoff, gbase, voff) do { _Pragma("unroll") for (int _i = 0; _i < 2; ++_i) \
;         __builtin_amdgcn_global_load_lds((const unsigned*)((const char*)(gbase) + (voff)[_i]), (LAS unsigned*)(lds + (bufoff) + ldsw + _i * 8192), 16, 0, 0); } while (0)
; #define PG8_WAIT_V(n) asm volatile("s_waitcnt vmcnt(" #n ")" ::: "memory")
; #define PG8_BAR __builtin_amdgcn_s_barrier()
; template <class Epi, class Sched>
; __device__ __forceinline__ void gemm_phase(LAS unsigned char* lds, const Gemm g, const Sched& S, const Epi& E) {
;     int tid = threadIdx.x; asm volatile("" : "+v"(tid));
;     const int wid = __builtin_amdgcn_readfirstlane(tid >> 6), lane = tid & 63, wr = wid >> 2, wc = wid & 3, fr = lane & 15, fq = lane >> 4;
;     int K = g.K; asm volatile("" : "+s"(K));
;     const int nt = K / BK;
;     unsigned voffA[2], voffB[2];
; #pragma unroll
;     for (int i = 0; i < 2; ++i) { int R, C; stage_rc(tid * 16 + i * 8192, R, C); const int Rb = Epi::PERM ? ((R & ~31) + perm32(R & 31)) : R;
;         voffA[i] = (unsigned)(R * K + C) * 2u; voffB[i] = (unsigned)(Rb * K + C) * 2u; }
;     const size_t kstep = (size_t)(BK * 2);
;     const size_t hstep = (size_t)HALF * K * 2;
;     const size_t tstep = 2 * hstep;
;     const unsigned ldsw = (unsigned)wid * 1024u;
;     const int aoff = lds_byte(wr * 64 + fr, fq * 8), boff = lds_byte(wc * 32 + fr, fq * 8);
;     ...
;     Unit cur, nxt; int ui = 0;
;     if (!S.next(0, cur)) return;
;     f32x4 acc[2][2][4][2];
; #pragma unroll
;     for (int a = 0; a < 2; ++a)
; #pragma unroll
;         for (int b = 0; b < 2; ++b)
; #pragma unroll
;             for (int m = 0; m < 4; ++m)
; #pragma unroll
;                 for (int n = 0; n < 2; ++n) acc[a][b][m][n] = (f32x4){0.f, 0.f, 0.f, 0.f};
;     bf16x8 At[4][2], B0[2][2], B1[2][2];
;     const char* cA = (const char*)g.A + (size_t)cur.pm * tstep; const char* cB = (const char*)g.Bt + (size_t)cur.pn * tstep;
;     S.a_ready(cur);
;     PG8_STAGE(PG8_SB(0, 0), cB, voffB); PG8_STAGE(PG8_SB(0, 1), cB + hstep, voffB); PG8_STAGE(PG8_SA(0, 0), cA, voffA); PG8_STAGE(PG8_SA(0, 1), cA + hstep, voffA);
;     if (wr == 1) PG8_BAR;
;     PG8_WAIT_V(2); PG8_BAR;
.LBB0_441:
	v_readlane_b32 s2, v249, 0
	v_readlane_b32 s3, v249, 1
	v_mov_b32_e32 v15, v189
	s_waitcnt vmcnt(0)
	s_barrier
	s_waitcnt vmcnt(0) lgkmcnt(0)
	s_barrier
	v_readfirstlane_b32 s98, v189
	s_nop 3
	s_cmp_ge_u32 s98, 64
	s_cbranch_scc1 .Lgrp_bar1_done
	s_lshr_b32 s98, s88, 21
	s_and_b32 s99, s98, 7
	s_lshr_b32 s98, s98, 5
	s_lshl_b32 s98, s98, 3
	s_or_b32 s98, s98, s99
	s_lshl_b32 s98, s98, 4
	v_readlane_b32 s99, v248, 36
	s_nop 3
	s_lshl_b32 s99, s99, 3
	s_add_u32 s98, s98, s99
	s_add_u32 s98, s98, 14336
	v_mov_b32_e32 v2, s98
	v_mov_b32_e32 v3, 1
	s_mov_b64 s[100:101], exec
	s_mov_b64 exec, 1
	buffer_wbl2 sc1
	s_waitcnt vmcnt(0)
	global_atomic_add v2, v3, s[80:81]
	s_mov_b32 s99, 0
.Lgrp_bar1_spin:
	s_sleep 1
	global_load_dword v4, v2, s[80:81] sc1
	s_add_u32 s99, s99, 1
	s_waitcnt vmcnt(0)
	v_readfirstlane_b32 s98, v4
	s_nop 3
	s_cmp_ge_u32 s98, 4
	s_cbranch_scc1 .Lgrp_bar1_got
	s_cmp_lt_u32 s99, 0x2000
	s_cbranch_scc1 .Lgrp_bar1_spin
.Lgrp_bar1_got:
	buffer_inv sc1
	s_waitcnt vmcnt(0)
	s_mov_b64 exec, s[100:101]
.Lgrp_bar1_done:
	s_barrier
	s_load_dwordx2 s[44:45], s[2:3], 0xf8
	s_movk_i32 s40, 0x1000
	v_lshlrev_b32_e32 v0, 4, v15
	v_add_u32_e32 v2, 0x2000, v0
	v_ashrrev_i32_e32 v3, 31, v2
	v_lshrrev_b32_e32 v3, 22, v3
	v_add_u32_e32 v3, v2, v3
	v_ashrrev_i32_e32 v3, 10, v3
	v_mul_i32_i24_e32 v4, 0x400, v3
	v_sub_u32_e32 v2, v2, v4
	v_lshrrev_b32_e32 v4, 4, v2
	s_waitcnt lgkmcnt(0)
	s_add_u32 s1, s44, s88
	v_bitop3_b32 v2, v4, v2, 32 bitop3:0x6c
	s_addc_u32 s3, s45, s89
	v_ashrrev_i32_e32 v4, 31, v2
	s_add_u32 s2, s1, 0xe000000
	v_lshrrev_b32_e32 v4, 26, v4
	s_addc_u32 s3, s3, 0
	s_and_b32 s98, s88, 0x3000000
	s_sub_u32 s2, s2, s98
	s_subb_u32 s3, s3, 0
	v_add_u32_e32 v4, v2, v4
	v_lshlrev_b32_e32 v6, 3, v3
	s_add_u32 s1, s44, s10
	v_ashrrev_i32_e32 v5, 6, v4
	v_and_b32_e32 v6, -16, v6
	v_lshlrev_b32_e32 v3, 5, v3
	s_addc_u32 s4, s45, s11
	v_add_u32_e32 v6, v5, v6
	v_and_b32_e32 v14, 32, v3
	v_and_b32_e32 v3, 0xc0, v4
	s_add_u32 s10, s1, 0x2000000
	v_and_b32_e32 v5, 3, v5
	s_mov_b32 s1, 0x7fffffe0
	v_lshrrev_b32_e32 v7, 2, v6
	v_lshlrev_b32_e32 v8, 1, v6
	v_sub_u32_e32 v2, v2, v3
	v_and_or_b32 v5, v6, s1, v5
	v_and_b32_e32 v7, 4, v7
	v_and_b32_e32 v8, 24, v8
	v_ashrrev_i16_sdwa v2, v227, sext(v2) dst_sel:DWORD dst_unused:UNUSED_PAD src0_sel:DWORD src1_sel:BYTE_0
	v_or3_b32 v5, v5, v7, v8
	v_bfe_i32 v16, v2, 0, 16
	v_add_u32_e32 v2, v14, v16
	v_mul_lo_u32 v5, v5, s40
	v_mul_lo_u32 v17, v6, s40
	v_add_lshl_u32 v142, v5, v2, 1
	v_add_lshl_u32 v144, v2, v17, 1
	v_bfe_i32 v2, v15, 27, 1
	v_lshrrev_b32_e32 v2, 22, v2
	v_add_u32_e32 v2, v0, v2
	v_and_b32_e32 v2, 0xfffffc00, v2
	v_sub_u32_e32 v0, v0, v2
	v_lshrrev_b32_e32 v2, 4, v0
	v_ashrrev_i32_e32 v4, 31, v15
	v_bitop3_b32 v0, v2, v0, 32 bitop3:0x6c
	v_lshrrev_b32_e32 v4, 26, v4
	v_ashrrev_i32_e32 v2, 31, v0
	v_add_u32_e32 v4, v15, v4
	v_lshrrev_b32_e32 v2, 26, v2
	v_ashrrev_i32_e32 v4, 6, v4
	v_add_u32_e32 v2, v0, v2
	v_lshlrev_b32_e32 v5, 3, v4
	v_ashrrev_i32_e32 v3, 6, v2
	v_and_b32_e32 v5, -16, v5
	v_add_u32_e32 v5, v3, v5
	v_and_b32_e32 v2, 0xc0, v2
	v_readfirstlane_b32 s8, v15
	v_and_b32_e32 v3, 3, v3
	v_lshrrev_b32_e32 v6, 2, v5
	v_lshlrev_b32_e32 v7, 1, v5
	v_sub_u32_e32 v0, v0, v2
	s_addc_u32 s11, s4, 0
	s_lshr_b32 s99, s98, 3
	s_add_u32 s10, s10, s99
	s_addc_u32 s11, s11, 0
	s_ashr_i32 s9, s8, 6
	v_and_or_b32 v3, v5, s1, v3
	v_and_b32_e32 v6, 4, v6
	v_and_b32_e32 v7, 24, v7
	v_lshlrev_b32_e32 v4, 5, v4
	v_ashrrev_i16_sdwa v0, v227, sext(v0) dst_sel:DWORD dst_unused:UNUSED_PAD src0_sel:DWORD src1_sel:BYTE_0
	s_lshl_b32 s4, s9, 10
	v_or3_b32 v3, v3, v6, v7
	v_and_b32_e32 v18, 32, v4
	v_bfe_i32 v19, v0, 0, 16
	v_mul_lo_u32 v3, v3, s40
	v_add_u32_e32 v2, v18, v19
	s_add_i32 s5, s4, 0
	s_ashr_i32 s41, s40, 31
	v_add_lshl_u32 v0, v3, v2, 1
	s_add_i32 m0, s5, 0x10000
	s_ashr_i32 s36, s8, 8
	s_lshl_b64 s[18:19], s[40:41], 8
	global_load_lds_dwordx4 v0, s[10:11]
	s_add_i32 m0, s5, 0x12000
	s_add_u32 s26, s10, s18
	global_load_lds_dwordx4 v142, s[10:11]
	s_addc_u32 s27, s11, s19
	s_add_i32 m0, s5, 0x14000
	v_mul_lo_u32 v20, v5, s40
	v_mov_b32_e32 v143, v1
	global_load_lds_dwordx4 v0, s[26:27]
	s_add_i32 m0, s5, 0x16000
	s_add_i32 s52, s5, 0x2000
	v_add_lshl_u32 v146, v2, v20, 1
	v_lshl_add_u64 v[6:7], s[26:27], 0, v[0:1]
	v_lshl_add_u64 v[8:9], s[26:27], 0, v[142:143]
	global_load_lds_dwordx4 v142, s[26:27]
	s_mov_b32 m0, s5
	s_add_u32 s26, s2, s18
	global_load_lds_dwordx4 v146, s[2:3]
	s_mov_b32 m0, s52
	s_addc_u32 s27, s3, s19
	s_add_i32 s53, s5, 0x4000
	global_load_lds_dwordx4 v144, s[2:3]
	s_mov_b32 m0, s53
	s_add_i32 s54, s5, 0x6000
	global_load_lds_dwordx4 v146, s[26:27]
	s_mov_b32 m0, s54
	v_mov_b32_e32 v147, v1
	global_load_lds_dwordx4 v144, s[26:27]
	v_mov_b32_e32 v145, v1
	s_cmp_eq_u32 s36, 1
	v_lshl_add_u64 v[2:3], s[10:11], 0, v[0:1]
	v_lshl_add_u64 v[4:5], s[10:11], 0, v[142:143]
	v_lshl_add_u64 v[10:11], s[2:3], 0, v[146:147]
	v_lshl_add_u64 v[12:13], s[2:3], 0, v[144:145]
	s_cselect_b64 s[26:27], -1, 0
	s_cmp_lg_u32 s36, 1
	s_cbranch_scc1 .LBB0_443
	s_barrier
; #define PG8_STAGE(bufoff, gbase, voff) do { _Pragma("unroll") for (int _i = 0; _i < 2; ++_i) \
;         __builtin_amdgcn_global_load_lds((const unsigned*)((const char*)(gbase) + (voff)[_i]), (LAS unsigned*)(lds + (bufoff) + ldsw + _i * 8192), 16, 0, 0); } while (0)
; #define PG8_WAIT_V(n) asm volatile("s_waitcnt vmcnt(" #n ")" ::: "memory")
; #define PG8_BAR __builtin_amdgcn_s_barrier()
; template <class Epi, class Sched>
; __device__ __forceinline__ void gemm_phase(LAS unsigned char* lds, const Gemm g, const Sched& S, const Epi& E) {
;     ...
;     PG8_STAGE(PG8_SB(1, 0), cB + kstep, voffB); PG8_STAGE(PG8_SA(1, 0), cA + kstep, voffA); PG8_STAGE(PG8_SB(1, 1), cB + hstep + kstep, voffB);
;     PG8_WAIT_V(6); PG8_BAR;
;     for (;;) {
;         const bool has_next = S.next(ui + 1, nxt);
;         const char* nA = has_next ? (const char*)g.A + (size_t)nxt.pm * tstep : cA; const char* nB = has_next ? (const char*)g.Bt + (size_t)nxt.pn * tstep : cB;
;         for (int t = 0; t < nt; t += 2) {
;     __device__ __forceinline__ void operator()(const f32x4 (&acc)[2][2][4][2], const Unit& u, int wr, int wc, int fr, int fq) const {
;         char* p = (char*)(HB + (size_t)(wr * 64 + fr) * ldc + u.pn * BM + wc * 32 + 8 * fq);
.LBB0_443:
	v_readlane_b32 s38, v249, 8
	v_readlane_b32 s39, v249, 9
	s_add_u32 s46, s44, s38
	s_addc_u32 s47, s45, s39
	s_add_i32 m0, s5, 0x18000
	v_lshl_add_u64 v[2:3], v[2:3], 0, s[6:7]
	s_waitcnt vmcnt(2)
	s_barrier
	global_load_lds_dwordx4 v[2:3], off
	v_lshl_add_u64 v[2:3], v[4:5], 0, s[6:7]
	s_add_i32 m0, s5, 0x1a000
	s_add_i32 s55, s5, 0x8000
	global_load_lds_dwordx4 v[2:3], off
	v_lshl_add_u64 v[2:3], v[10:11], 0, s[6:7]
	s_mov_b32 m0, s55
	s_add_i32 s56, s5, 0xa000
	global_load_lds_dwordx4 v[2:3], off
	v_lshl_add_u64 v[2:3], v[12:13], 0, s[6:7]
	s_mov_b32 m0, s56
	s_lshr_b32 s1, s41, 26
	global_load_lds_dwordx4 v[2:3], off
	s_add_i32 m0, s5, 0x1c000
	v_lshl_add_u64 v[2:3], v[6:7], 0, s[6:7]
	global_load_lds_dwordx4 v[2:3], off
	v_lshl_add_u64 v[2:3], v[8:9], 0, s[6:7]
	s_add_i32 m0, s5, 0x1e000
	s_add_i32 s1, s40, s1
	global_load_lds_dwordx4 v[2:3], off
	v_and_b32_e32 v3, 15, v15
	v_and_b32_e32 v4, 48, v15
	v_lshlrev_b32_e32 v5, 2, v15
	s_ashr_i32 s57, s1, 6
	v_lshl_or_b32 v2, s36, 6, v3
	v_lshl_or_b32 v3, v3, 6, v4
	s_lshl_b32 s1, s36, 13
	v_and_b32_e32 v5, 32, v5
	v_bitop3_b32 v6, v3, s1, v5 bitop3:0xde
	s_lshl_b32 s1, s9, 5
	s_and_b32 s1, s1, 0x60
	s_lshl_b64 s[38:39], s[40:41], 9
	s_lshl_b32 s9, s1, 7
	s_cmp_gt_i32 s40, 63
	v_bitop3_b32 v160, v3, s9, v5 bitop3:0xde
	s_cselect_b64 s[40:41], -1, 0
	s_add_i32 s58, s57, -2
	v_ashrrev_i32_e32 v3, 31, v2
	s_cmpk_lt_u32 s8, 0x100
	v_lshlrev_b64 v[2:3], 11, v[2:3]
	s_cselect_b64 s[42:43], -1, 0
	v_lshl_add_u64 v[2:3], s[46:47], 0, v[2:3]
	s_lshl_b32 s36, s1, 1
	v_lshl_add_u64 v[2:3], v[2:3], 0, s[36:37]
	v_mov_b32_e32 v5, v1
	v_lshl_add_u64 v[2:3], v[2:3], 0, v[4:5]
	s_mov_b64 s[8:9], 0x6000000
	v_readlane_b32 s1, v248, 24
	v_lshl_add_u64 v[148:149], v[2:3], 0, s[8:9]
	s_lshr_b32 s100, s98, 15
	s_lshr_b32 s99, s98, 2
	s_sub_u32 s100, s100, s99
	s_subb_u32 s101, 0, 0
	v_lshl_add_u64 v[148:149], v[148:149], 0, s[100:101]
	s_add_u32 s1, s44, s1
	v_readlane_b32 s8, v248, 25
	s_addc_u32 s9, s45, s8
	v_add_u32_e32 v2, v20, v18
	s_add_u32 s8, s1, s18
	v_add_lshl_u32 v2, v2, v19, 1
	v_mov_b32_e32 v3, v1
	s_addc_u32 s9, s9, s19
	s_sub_u32 s8, s8, s98
	s_subb_u32 s9, s9, 0
	s_waitcnt vmcnt(6)
	v_lshl_add_u64 v[150:151], s[8:9], 0, v[2:3]
	v_add_u32_e32 v2, v17, v14
	v_add_lshl_u32 v2, v2, v16, 1
	v_lshl_add_u64 v[152:153], s[8:9], 0, v[2:3]
	s_mov_b32 s8, 0
	v_add_u32_e32 v161, 0, v6
	s_mov_b64 s[46:47], s[10:11]
	s_mov_b64 s[44:45], s[10:11]
	s_barrier
	s_branch .LBB0_446

; template <class Epi, class Sched>
; __device__ __forceinline__ void gemm_phase(LAS unsigned char* lds, const Gemm g, const Sched& S, const Epi& E) {
;     ...
;         const bool has_next = S.next(ui + 1, nxt);
;         const char* nA = has_next ? (const char*)g.A + (size_t)nxt.pm * tstep : cA; const char* nB = has_next ? (const char*)g.Bt + (size_t)nxt.pn * tstep : cB;
;         for (int t = 0; t < nt; t += 2) {
;             const bool last = (t == nt - 2);
;             const char* a1 = cA + (size_t)(t + 1) * kstep;
;             const char* a2 = last ? nA : cA + (size_t)(t + 2) * kstep; const char* b2 = last ? nB : cB + (size_t)(t + 2) * kstep;
;             const char* a3 = a2 + kstep; const char* b3 = b2 + kstep;
;             if (last && has_next) S.a_ready(nxt);
;     ...
;         cur = nxt; cA = nA; cB = nB; ++ui;
.LBB0_445:
	s_andn2_b64 vcc, exec, s[8:9]
	s_add_u32 s2, s2, 0x1000000
	s_addc_u32 s3, s3, 0
	s_mov_b32 s100, 0x1000000
	s_mov_b32 s101, 0
	v_lshl_add_u64 v[150:151], v[150:151], 0, s[100:101]
	v_lshl_add_u64 v[152:153], v[152:153], 0, s[100:101]
	s_mov_b32 s8, s59
	s_mov_b64 s[46:47], s[44:45]
	s_cbranch_vccz .LBB0_456
.LBB0_446:
	s_add_i32 s59, s8, 1
	s_cmp_gt_u32 s8, 2
	s_cbranch_scc1 .LBB0_448
	s_mov_b64 s[44:45], s[10:11]

; #define PG8_STAGE(bufoff, gbase, voff) do { _Pragma("unroll") for (int _i = 0; _i < 2; ++_i) \
;         __builtin_amdgcn_global_load_lds((const unsigned*)((const char*)(gbase) + (voff)[_i]), (LAS unsigned*)(lds + (bufoff) + ldsw + _i * 8192), 16, 0, 0); } while (0)
; #define PG8_LDA(dst, b, h) do { _Pragma("unroll") for (int m = 0; m < 4; ++m) _Pragma("unroll") for (int k = 0; k < 2; ++k) dst[m][k] = *(const LAS bf16x8*)(lds + PG8_SA(b, h) + aoff + m * 2048 + k * 1024); } while (0)
; #define PG8_LDB(dst, b, h) do { _Pragma("unroll") for (int n = 0; n < 2; ++n) _Pragma("unroll") for (int k = 0; k < 2; ++k) dst[n][k] = *(const LAS bf16x8*)(lds + PG8_SB(b, h) + boff + n * 2048 + k * 1024); } while (0)
; #define PG8_MMA(ai, bj, At, Bt) do { __builtin_amdgcn_s_setprio(1); _Pragma("unroll") for (int m = 0; m < 4; ++m) _Pragma("unroll") for (int n = 0; n < 2; ++n) _Pragma("unroll") for (int k = 0; k < 2; ++k) \
;         acc[ai][bj][m][n] = __builtin_amdgcn_mfma_f32_16x16x32_bf16(Bt[n][k], At[m][k], acc[ai][bj][m][n], 0, 0, 0); __builtin_amdgcn_s_setprio(0); } while (0)
; #define PG8_WAIT_V(n) asm volatile("s_waitcnt vmcnt(" #n ")" ::: "memory")
; #define PG8_WAIT_L(n) asm volatile("s_waitcnt lgkmcnt(" #n ")" ::: "memory")
; #define PG8_BAR __builtin_amdgcn_s_barrier()
; template <class Epi, class Sched>
; __device__ __forceinline__ void gemm_phase(LAS unsigned char* lds, const Gemm g, const Sched& S, const Epi& E) {
;     ...
;         for (int t = 0; t < nt; t += 2) {
;             const bool last = (t == nt - 2);
;             const char* a1 = cA + (size_t)(t + 1) * kstep;
;             const char* a2 = last ? nA : cA + (size_t)(t + 2) * kstep; const char* b2 = last ? nB : cB + (size_t)(t + 2) * kstep;
;             const char* a3 = a2 + kstep; const char* b3 = b2 + kstep;
;             if (last && has_next) S.a_ready(nxt);
;             PG8_LDB(B0, 0, 0); PG8_LDB(B1, 0, 1); PG8_SCHED; PG8_LDA(At, 0, 0); PG8_STAGE(PG8_SA(1, 1), a1 + hstep, voffA);
;             PG8_WAIT_V(8); PG8_WAIT_L(0); PG8_BAR; PG8_MMA(0, 0, At, B0); PG8_MMA(0, 1, At, B1); PG8_BAR; PG8_SCHED;
;             PG8_LDA(At, 0, 1); PG8_STAGE(PG8_SB(0, 0), b2, voffB); PG8_STAGE(PG8_SB(0, 1), b2 + hstep, voffB); PG8_STAGE(PG8_SA(0, 0), a2, voffA);
;             PG8_WAIT_V(8); PG8_WAIT_L(0); PG8_BAR; PG8_MMA(1, 0, At, B0); PG8_MMA(1, 1, At, B1); PG8_BAR; PG8_SCHED;
.LBB0_450:
	s_add_i32 s60, s50, 2
	s_add_u32 s48, s46, 0x100
	s_addc_u32 s49, s47, 0
	s_add_u32 s1, s9, s46
	s_addc_u32 s51, s36, s47
	s_cmp_eq_u32 s58, s50
	s_cselect_b32 s50, 0x1000000, s48
	s_cselect_b32 s61, 0, s49
	s_cselect_b32 s62, s44, s1
	s_cselect_b32 s63, s45, s51
	s_add_u32 s50, s2, s50
	s_addc_u32 s51, s3, s61
	s_add_i32 s1, 0, 0x10000
	s_add_i32 s61, 0, 0x14000
	v_add_u32_e32 v154, s1, v160
	v_add_u32_e32 v158, s61, v160
	ds_read_b128 v[130:133], v154
	ds_read_b128 v[134:137], v154 offset:1024
	ds_read_b128 v[138:141], v154 offset:2048
	ds_read_b128 v[154:157], v154 offset:3072
	ds_read_b128 v[162:165], v158
	ds_read_b128 v[166:169], v158 offset:1024
	ds_read_b128 v[170:173], v158 offset:2048
	ds_read_b128 v[174:177], v158 offset:3072
	v_lshl_add_u64 v[158:159], v[150:151], 0, s[46:47]
	s_add_i32 m0, s5, 0xc000
	ds_read_b128 v[178:181], v161
	ds_read_b128 v[182:185], v161 offset:1024
	ds_read_b128 v[192:195], v161 offset:2048
	ds_read_b128 v[196:199], v161 offset:3072
	ds_read_b128 v[200:203], v161 offset:4096
	ds_read_b128 v[204:207], v161 offset:5120
	ds_read_b128 v[208:211], v161 offset:6144
	ds_read_b128 v[212:215], v161 offset:7168
	global_load_lds_dwordx4 v[158:159], off
	v_lshl_add_u64 v[158:159], v[152:153], 0, s[46:47]
	s_add_i32 m0, s5, 0xe000
	s_nop 0
	global_load_lds_dwordx4 v[158:159], off
	s_waitcnt vmcnt(8)
	s_waitcnt lgkmcnt(0)
	s_barrier
	s_setprio 1
	s_waitcnt lgkmcnt(0)
	v_mfma_f32_16x16x32_bf16 v[122:125], v[130:133], v[178:181], v[122:125]
	v_mfma_f32_16x16x32_bf16 v[126:129], v[138:141], v[178:181], v[126:129]
	v_mfma_f32_16x16x32_bf16 v[110:113], v[130:133], v[192:195], v[110:113]
	v_mfma_f32_16x16x32_bf16 v[106:109], v[138:141], v[192:195], v[106:109]
	v_mfma_f32_16x16x32_bf16 v[94:97], v[130:133], v[200:203], v[94:97]
	v_mfma_f32_16x16x32_bf16 v[90:93], v[138:141], v[200:203], v[90:93]
	v_mfma_f32_16x16x32_bf16 v[78:81], v[130:133], v[208:211], v[78:81]
	v_mfma_f32_16x16x32_bf16 v[74:77], v[138:141], v[208:211], v[74:77]
	v_mfma_f32_16x16x32_bf16 v[122:125], v[134:137], v[182:185], v[122:125]
	v_mfma_f32_16x16x32_bf16 v[126:129], v[154:157], v[182:185], v[126:129]
	v_mfma_f32_16x16x32_bf16 v[110:113], v[134:137], v[196:199], v[110:113]
	v_mfma_f32_16x16x32_bf16 v[106:109], v[154:157], v[196:199], v[106:109]
	v_mfma_f32_16x16x32_bf16 v[94:97], v[134:137], v[204:207], v[94:97]
	v_mfma_f32_16x16x32_bf16 v[90:93], v[154:157], v[204:207], v[90:93]
	v_mfma_f32_16x16x32_bf16 v[78:81], v[134:137], v[212:215], v[78:81]
	v_mfma_f32_16x16x32_bf16 v[74:77], v[154:157], v[212:215], v[74:77]
	s_setprio 0
	s_setprio 1
	v_mfma_f32_16x16x32_bf16 v[118:121], v[162:165], v[178:181], v[118:121]
	v_mfma_f32_16x16x32_bf16 v[114:117], v[170:173], v[178:181], v[114:117]
	v_mfma_f32_16x16x32_bf16 v[102:105], v[162:165], v[192:195], v[102:105]
	v_mfma_f32_16x16x32_bf16 v[98:101], v[170:173], v[192:195], v[98:101]
	v_mfma_f32_16x16x32_bf16 v[86:89], v[162:165], v[200:203], v[86:89]
	v_mfma_f32_16x16x32_bf16 v[82:85], v[170:173], v[200:203], v[82:85]
	v_mfma_f32_16x16x32_bf16 v[70:73], v[162:165], v[208:211], v[70:73]
	v_mfma_f32_16x16x32_bf16 v[66:69], v[170:173], v[208:211], v[66:69]
	v_mfma_f32_16x16x32_bf16 v[118:121], v[166:169], v[182:185], v[118:121]
	v_mfma_f32_16x16x32_bf16 v[114:117], v[174:177], v[182:185], v[114:117]
	v_mfma_f32_16x16x32_bf16 v[102:105], v[166:169], v[196:199], v[102:105]
	v_mfma_f32_16x16x32_bf16 v[98:101], v[174:177], v[196:199], v[98:101]
	v_mfma_f32_16x16x32_bf16 v[86:89], v[166:169], v[204:207], v[86:89]
	v_mfma_f32_16x16x32_bf16 v[82:85], v[174:177], v[204:207], v[82:85]
	v_mfma_f32_16x16x32_bf16 v[70:73], v[166:169], v[212:215], v[70:73]
	v_mfma_f32_16x16x32_bf16 v[66:69], v[174:177], v[212:215], v[66:69]
	s_setprio 0
	s_barrier
	s_add_i32 s1, s1, s4
	v_lshl_add_u64 v[158:159], s[62:63], 0, v[0:1]
	s_mov_b32 m0, s1
	ds_read_b128 v[178:181], v161 offset:16384
	ds_read_b128 v[182:185], v161 offset:17408
	ds_read_b128 v[192:195], v161 offset:18432
	ds_read_b128 v[196:199], v161 offset:19456
	ds_read_b128 v[200:203], v161 offset:20480
	ds_read_b128 v[204:207], v161 offset:21504
	ds_read_b128 v[208:211], v161 offset:22528
	ds_read_b128 v[212:215], v161 offset:23552
	global_load_lds_dwordx4 v[158:159], off
	s_add_i32 m0, s1, 0x2000
	s_add_u32 s46, s62, s18
	v_lshl_add_u64 v[186:187], s[62:63], 0, v[142:143]
	s_addc_u32 s47, s63, s19
	s_add_i32 s1, s61, s4
	global_load_lds_dwordx4 v[186:187], off
	v_lshl_add_u64 v[216:217], s[46:47], 0, v[0:1]
	s_mov_b32 m0, s1
	v_lshl_add_u64 v[238:239], s[46:47], 0, v[142:143]
	global_load_lds_dwordx4 v[216:217], off
	s_add_i32 m0, s1, 0x2000
	v_lshl_add_u64 v[240:241], s[50:51], 0, v[146:147]
	global_load_lds_dwordx4 v[238:239], off
	s_mov_b32 m0, s5
	v_lshl_add_u64 v[244:245], s[50:51], 0, v[144:145]
	global_load_lds_dwordx4 v[240:241], off
	s_mov_b32 m0, s52
	s_nop 0
	global_load_lds_dwordx4 v[244:245], off
	s_waitcnt vmcnt(8)
	s_waitcnt lgkmcnt(0)
	s_barrier
; #define PG8_STAGE(bufoff, gbase, voff) do { _Pragma("unroll") for (int _i = 0; _i < 2; ++_i) \
;         __builtin_amdgcn_global_load_lds((const unsigned*)((const char*)(gbase) + (voff)[_i]), (LAS unsigned*)(lds + (bufoff) + ldsw + _i * 8192), 16, 0, 0); } while (0)
; #define PG8_LDA(dst, b, h) do { _Pragma("unroll") for (int m = 0; m < 4; ++m) _Pragma("unroll") for (int k = 0; k < 2; ++k) dst[m][k] = *(const LAS bf16x8*)(lds + PG8_SA(b, h) + aoff + m * 2048 + k * 1024); } while (0)
; #define PG8_LDB(dst, b, h) do { _Pragma("unroll") for (int n = 0; n < 2; ++n) _Pragma("unroll") for (int k = 0; k < 2; ++k) dst[n][k] = *(const LAS bf16x8*)(lds + PG8_SB(b, h) + boff + n * 2048 + k * 1024); } while (0)
; #define PG8_MMA(ai, bj, At, Bt) do { __builtin_amdgcn_s_setprio(1); _Pragma("unroll") for (int m = 0; m < 4; ++m) _Pragma("unroll") for (int n = 0; n < 2; ++n) _Pragma("unroll") for (int k = 0; k < 2; ++k) \
;         acc[ai][bj][m][n] = __builtin_amdgcn_mfma_f32_16x16x32_bf16(Bt[n][k], At[m][k], acc[ai][bj][m][n], 0, 0, 0); __builtin_amdgcn_s_setprio(0); } while (0)
; #define PG8_WAIT_V(n) asm volatile("s_waitcnt vmcnt(" #n ")" ::: "memory")
; #define PG8_WAIT_L(n) asm volatile("s_waitcnt lgkmcnt(" #n ")" ::: "memory")
; #define PG8_BAR __builtin_amdgcn_s_barrier()
; #define PG8_SCHED __builtin_amdgcn_sched_barrier(0)
; template <class Epi, class Sched>
; __device__ __forceinline__ void gemm_phase(LAS unsigned char* lds, const Gemm g, const Sched& S, const Epi& E) {
;     ...
;             PG8_WAIT_V(8); PG8_WAIT_L(0); PG8_BAR; PG8_MMA(1, 0, At, B0); PG8_MMA(1, 1, At, B1); PG8_BAR; PG8_SCHED;
;             PG8_LDB(B0, 1, 0); PG8_LDB(B1, 1, 1); PG8_SCHED; PG8_LDA(At, 1, 0); PG8_STAGE(PG8_SA(0, 1), a2 + hstep, voffA);
;             PG8_WAIT_V(8); PG8_WAIT_L(0); PG8_BAR; PG8_MMA(0, 0, At, B0); PG8_MMA(0, 1, At, B1); PG8_BAR; PG8_SCHED;
	s_setprio 1
	s_waitcnt lgkmcnt(0)
	v_mfma_f32_16x16x32_bf16 v[62:65], v[130:133], v[178:181], v[62:65]
	v_mfma_f32_16x16x32_bf16 v[58:61], v[138:141], v[178:181], v[58:61]
	v_mfma_f32_16x16x32_bf16 v[46:49], v[130:133], v[192:195], v[46:49]
	v_mfma_f32_16x16x32_bf16 v[42:45], v[138:141], v[192:195], v[42:45]
	v_mfma_f32_16x16x32_bf16 v[30:33], v[130:133], v[200:203], v[30:33]
	v_mfma_f32_16x16x32_bf16 v[26:29], v[138:141], v[200:203], v[26:29]
	v_mfma_f32_16x16x32_bf16 v[14:17], v[130:133], v[208:211], v[14:17]
	v_mfma_f32_16x16x32_bf16 v[10:13], v[138:141], v[208:211], v[10:13]
	v_mfma_f32_16x16x32_bf16 v[62:65], v[134:137], v[182:185], v[62:65]
	v_mfma_f32_16x16x32_bf16 v[58:61], v[154:157], v[182:185], v[58:61]
	v_mfma_f32_16x16x32_bf16 v[46:49], v[134:137], v[196:199], v[46:49]
	v_mfma_f32_16x16x32_bf16 v[42:45], v[154:157], v[196:199], v[42:45]
	v_mfma_f32_16x16x32_bf16 v[30:33], v[134:137], v[204:207], v[30:33]
	v_mfma_f32_16x16x32_bf16 v[26:29], v[154:157], v[204:207], v[26:29]
	v_mfma_f32_16x16x32_bf16 v[14:17], v[134:137], v[212:215], v[14:17]
	v_mfma_f32_16x16x32_bf16 v[10:13], v[154:157], v[212:215], v[10:13]
	s_setprio 0
	s_setprio 1
	v_mfma_f32_16x16x32_bf16 v[54:57], v[162:165], v[178:181], v[54:57]
	v_mfma_f32_16x16x32_bf16 v[50:53], v[170:173], v[178:181], v[50:53]
	v_mfma_f32_16x16x32_bf16 v[38:41], v[162:165], v[192:195], v[38:41]
	v_mfma_f32_16x16x32_bf16 v[34:37], v[170:173], v[192:195], v[34:37]
	v_mfma_f32_16x16x32_bf16 v[22:25], v[162:165], v[200:203], v[22:25]
	v_mfma_f32_16x16x32_bf16 v[18:21], v[170:173], v[200:203], v[18:21]
	v_mfma_f32_16x16x32_bf16 v[6:9], v[162:165], v[208:211], v[6:9]
	v_mfma_f32_16x16x32_bf16 v[2:5], v[170:173], v[208:211], v[2:5]
	v_mfma_f32_16x16x32_bf16 v[54:57], v[166:169], v[182:185], v[54:57]
	v_mfma_f32_16x16x32_bf16 v[50:53], v[174:177], v[182:185], v[50:53]
	v_mfma_f32_16x16x32_bf16 v[38:41], v[166:169], v[196:199], v[38:41]
	v_mfma_f32_16x16x32_bf16 v[34:37], v[174:177], v[196:199], v[34:37]
	v_mfma_f32_16x16x32_bf16 v[22:25], v[166:169], v[204:207], v[22:25]
	v_mfma_f32_16x16x32_bf16 v[18:21], v[174:177], v[204:207], v[18:21]
	v_mfma_f32_16x16x32_bf16 v[6:9], v[166:169], v[212:215], v[6:9]
	v_mfma_f32_16x16x32_bf16 v[2:5], v[174:177], v[212:215], v[2:5]
	s_setprio 0
	s_barrier
	s_add_i32 s1, 0, 0x18000
	s_add_i32 s61, 0, 0x1c000
	v_add_u32_e32 v154, s1, v160
	v_add_u32_e32 v174, s61, v160
	ds_read_b128 v[130:133], v154
	ds_read_b128 v[134:137], v154 offset:1024
	ds_read_b128 v[138:141], v154 offset:2048
	ds_read_b128 v[154:157], v154 offset:3072
	ds_read_b128 v[162:165], v174
	ds_read_b128 v[166:169], v174 offset:1024
	ds_read_b128 v[170:173], v174 offset:2048
	ds_read_b128 v[174:177], v174 offset:3072
	s_add_u32 s46, s50, s18
	s_addc_u32 s47, s51, s19
	s_mov_b32 m0, s53
	v_lshl_add_u64 v[246:247], s[46:47], 0, v[146:147]
	ds_read_b128 v[178:181], v161 offset:32768
	ds_read_b128 v[182:185], v161 offset:33792
	ds_read_b128 v[192:195], v161 offset:34816
	ds_read_b128 v[196:199], v161 offset:35840
	ds_read_b128 v[200:203], v161 offset:36864
	ds_read_b128 v[204:207], v161 offset:37888
	ds_read_b128 v[208:211], v161 offset:38912
	ds_read_b128 v[212:215], v161 offset:39936
	global_load_lds_dwordx4 v[246:247], off
	v_lshl_add_u64 v[246:247], s[46:47], 0, v[144:145]
	s_mov_b32 m0, s54
	s_nop 0
	global_load_lds_dwordx4 v[246:247], off
	s_waitcnt vmcnt(8)
	s_waitcnt lgkmcnt(0)
	s_barrier
	s_setprio 1
	s_waitcnt lgkmcnt(0)
	v_mfma_f32_16x16x32_bf16 v[122:125], v[130:133], v[178:181], v[122:125]
	v_mfma_f32_16x16x32_bf16 v[126:129], v[138:141], v[178:181], v[126:129]
	v_mfma_f32_16x16x32_bf16 v[110:113], v[130:133], v[192:195], v[110:113]
	v_mfma_f32_16x16x32_bf16 v[106:109], v[138:141], v[192:195], v[106:109]
	v_mfma_f32_16x16x32_bf16 v[94:97], v[130:133], v[200:203], v[94:97]
	v_mfma_f32_16x16x32_bf16 v[90:93], v[138:141], v[200:203], v[90:93]
	v_mfma_f32_16x16x32_bf16 v[78:81], v[130:133], v[208:211], v[78:81]
	v_mfma_f32_16x16x32_bf16 v[74:77], v[138:141], v[208:211], v[74:77]
	v_mfma_f32_16x16x32_bf16 v[122:125], v[134:137], v[182:185], v[122:125]
	v_mfma_f32_16x16x32_bf16 v[126:129], v[154:157], v[182:185], v[126:129]
	v_mfma_f32_16x16x32_bf16 v[110:113], v[134:137], v[196:199], v[110:113]
	v_mfma_f32_16x16x32_bf16 v[106:109], v[154:157], v[196:199], v[106:109]
	v_mfma_f32_16x16x32_bf16 v[94:97], v[134:137], v[204:207], v[94:97]
	v_mfma_f32_16x16x32_bf16 v[90:93], v[154:157], v[204:207], v[90:93]
	v_mfma_f32_16x16x32_bf16 v[78:81], v[134:137], v[212:215], v[78:81]
	v_mfma_f32_16x16x32_bf16 v[74:77], v[154:157], v[212:215], v[74:77]
	s_setprio 0
	s_setprio 1
	v_mfma_f32_16x16x32_bf16 v[118:121], v[162:165], v[178:181], v[118:121]
	v_mfma_f32_16x16x32_bf16 v[114:117], v[170:173], v[178:181], v[114:117]
	v_mfma_f32_16x16x32_bf16 v[102:105], v[162:165], v[192:195], v[102:105]
	v_mfma_f32_16x16x32_bf16 v[98:101], v[170:173], v[192:195], v[98:101]
	v_mfma_f32_16x16x32_bf16 v[86:89], v[162:165], v[200:203], v[86:89]
	v_mfma_f32_16x16x32_bf16 v[82:85], v[170:173], v[200:203], v[82:85]
	v_mfma_f32_16x16x32_bf16 v[70:73], v[162:165], v[208:211], v[70:73]
	v_mfma_f32_16x16x32_bf16 v[66:69], v[170:173], v[208:211], v[66:69]
	v_mfma_f32_16x16x32_bf16 v[118:121], v[166:169], v[182:185], v[118:121]
	v_mfma_f32_16x16x32_bf16 v[114:117], v[174:177], v[182:185], v[114:117]
	v_mfma_f32_16x16x32_bf16 v[102:105], v[166:169], v[196:199], v[102:105]
	v_mfma_f32_16x16x32_bf16 v[98:101], v[174:177], v[196:199], v[98:101]
	v_mfma_f32_16x16x32_bf16 v[86:89], v[166:169], v[204:207], v[86:89]
	v_mfma_f32_16x16x32_bf16 v[82:85], v[174:177], v[204:207], v[82:85]
	v_mfma_f32_16x16x32_bf16 v[70:73], v[166:169], v[212:215], v[70:73]
	v_mfma_f32_16x16x32_bf16 v[66:69], v[174:177], v[212:215], v[66:69]
	s_setprio 0
	s_barrier
; #define PG8_STAGE(bufoff, gbase, voff) do { _Pragma("unroll") for (int _i = 0; _i < 2; ++_i) \
;         __builtin_amdgcn_global_load_lds((const unsigned*)((const char*)(gbase) + (voff)[_i]), (LAS unsigned*)(lds + (bufoff) + ldsw + _i * 8192), 16, 0, 0); } while (0)
; #define PG8_LDA(dst, b, h) do { _Pragma("unroll") for (int m = 0; m < 4; ++m) _Pragma("unroll") for (int k = 0; k < 2; ++k) dst[m][k] = *(const LAS bf16x8*)(lds + PG8_SA(b, h) + aoff + m * 2048 + k * 1024); } while (0)
; #define PG8_MMA(ai, bj, At, Bt) do { __builtin_amdgcn_s_setprio(1); _Pragma("unroll") for (int m = 0; m < 4; ++m) _Pragma("unroll") for (int n = 0; n < 2; ++n) _Pragma("unroll") for (int k = 0; k < 2; ++k) \
;         acc[ai][bj][m][n] = __builtin_amdgcn_mfma_f32_16x16x32_bf16(Bt[n][k], At[m][k], acc[ai][bj][m][n], 0, 0, 0); __builtin_amdgcn_s_setprio(0); } while (0)
; #define PG8_WAIT_V(n) asm volatile("s_waitcnt vmcnt(" #n ")" ::: "memory")
; #define PG8_WAIT_L(n) asm volatile("s_waitcnt lgkmcnt(" #n ")" ::: "memory")
; #define PG8_BAR __builtin_amdgcn_s_barrier()
; #define PG8_SCHED __builtin_amdgcn_sched_barrier(0)
; template <class Epi, class Sched>
; __device__ __forceinline__ void gemm_phase(LAS unsigned char* lds, const Gemm g, const Sched& S, const Epi& E) {
;     ...
;             PG8_WAIT_V(8); PG8_WAIT_L(0); PG8_BAR; PG8_MMA(0, 0, At, B0); PG8_MMA(0, 1, At, B1); PG8_BAR; PG8_SCHED;
;             PG8_LDA(At, 1, 1); PG8_STAGE(PG8_SB(1, 0), b3, voffB); PG8_STAGE(PG8_SB(1, 1), b3 + hstep, voffB); PG8_STAGE(PG8_SA(1, 0), a3, voffA);
;             PG8_WAIT_V(8); PG8_WAIT_L(0); PG8_BAR; PG8_MMA(1, 0, At, B0); PG8_MMA(1, 1, At, B1); PG8_BAR; PG8_SCHED;
;         }
	s_add_i32 s1, s1, s4
	v_lshl_add_u64 v[158:159], v[158:159], 0, s[6:7]
	s_mov_b32 m0, s1
	ds_read_b128 v[178:181], v161 offset:49152
	ds_read_b128 v[182:185], v161 offset:50176
	ds_read_b128 v[192:195], v161 offset:51200
	ds_read_b128 v[196:199], v161 offset:52224
	ds_read_b128 v[200:203], v161 offset:53248
	ds_read_b128 v[204:207], v161 offset:54272
	ds_read_b128 v[208:211], v161 offset:55296
	ds_read_b128 v[212:215], v161 offset:56320
	global_load_lds_dwordx4 v[158:159], off
	v_lshl_add_u64 v[158:159], v[186:187], 0, s[6:7]
	s_add_i32 m0, s1, 0x2000
	s_add_i32 s1, s61, s4
	global_load_lds_dwordx4 v[158:159], off
	v_lshl_add_u64 v[158:159], v[216:217], 0, s[6:7]
	s_mov_b32 m0, s1
	s_nop 0
	global_load_lds_dwordx4 v[158:159], off
	v_lshl_add_u64 v[158:159], v[238:239], 0, s[6:7]
	s_add_i32 m0, s1, 0x2000
	s_nop 0
	global_load_lds_dwordx4 v[158:159], off
	v_lshl_add_u64 v[158:159], v[240:241], 0, s[6:7]
	s_mov_b32 m0, s55
	s_nop 0
	global_load_lds_dwordx4 v[158:159], off
	v_lshl_add_u64 v[158:159], v[244:245], 0, s[6:7]
	s_mov_b32 m0, s56
	s_nop 0
	global_load_lds_dwordx4 v[158:159], off
	s_waitcnt vmcnt(8)
	s_waitcnt lgkmcnt(0)
	s_barrier
	s_setprio 1
	s_waitcnt lgkmcnt(0)
	v_mfma_f32_16x16x32_bf16 v[62:65], v[130:133], v[178:181], v[62:65]
	v_mfma_f32_16x16x32_bf16 v[58:61], v[138:141], v[178:181], v[58:61]
	v_mfma_f32_16x16x32_bf16 v[46:49], v[130:133], v[192:195], v[46:49]
	v_mfma_f32_16x16x32_bf16 v[42:45], v[138:141], v[192:195], v[42:45]
	v_mfma_f32_16x16x32_bf16 v[30:33], v[130:133], v[200:203], v[30:33]
	v_mfma_f32_16x16x32_bf16 v[26:29], v[138:141], v[200:203], v[26:29]
	v_mfma_f32_16x16x32_bf16 v[14:17], v[130:133], v[208:211], v[14:17]
	v_mfma_f32_16x16x32_bf16 v[10:13], v[138:141], v[208:211], v[10:13]
	v_mfma_f32_16x16x32_bf16 v[62:65], v[134:137], v[182:185], v[62:65]
	v_mfma_f32_16x16x32_bf16 v[58:61], v[154:157], v[182:185], v[58:61]
	v_mfma_f32_16x16x32_bf16 v[46:49], v[134:137], v[196:199], v[46:49]
	v_mfma_f32_16x16x32_bf16 v[42:45], v[154:157], v[196:199], v[42:45]
	v_mfma_f32_16x16x32_bf16 v[30:33], v[134:137], v[204:207], v[30:33]
	v_mfma_f32_16x16x32_bf16 v[26:29], v[154:157], v[204:207], v[26:29]
	v_mfma_f32_16x16x32_bf16 v[14:17], v[134:137], v[212:215], v[14:17]
	v_mfma_f32_16x16x32_bf16 v[10:13], v[154:157], v[212:215], v[10:13]
	s_setprio 0
	s_setprio 1
	v_mfma_f32_16x16x32_bf16 v[54:57], v[162:165], v[178:181], v[54:57]
	v_mfma_f32_16x16x32_bf16 v[50:53], v[170:173], v[178:181], v[50:53]
	v_mfma_f32_16x16x32_bf16 v[38:41], v[162:165], v[192:195], v[38:41]
	v_mfma_f32_16x16x32_bf16 v[34:37], v[170:173], v[192:195], v[34:37]
	v_mfma_f32_16x16x32_bf16 v[22:25], v[162:165], v[200:203], v[22:25]
	v_mfma_f32_16x16x32_bf16 v[18:21], v[170:173], v[200:203], v[18:21]
	v_mfma_f32_16x16x32_bf16 v[6:9], v[162:165], v[208:211], v[6:9]
	v_mfma_f32_16x16x32_bf16 v[2:5], v[170:173], v[208:211], v[2:5]
	v_mfma_f32_16x16x32_bf16 v[54:57], v[166:169], v[182:185], v[54:57]
	v_mfma_f32_16x16x32_bf16 v[50:53], v[174:177], v[182:185], v[50:53]
	v_mfma_f32_16x16x32_bf16 v[38:41], v[166:169], v[196:199], v[38:41]
	v_mfma_f32_16x16x32_bf16 v[34:37], v[174:177], v[196:199], v[34:37]
	v_mfma_f32_16x16x32_bf16 v[22:25], v[166:169], v[204:207], v[22:25]
	v_mfma_f32_16x16x32_bf16 v[18:21], v[174:177], v[204:207], v[18:21]
	v_mfma_f32_16x16x32_bf16 v[6:9], v[166:169], v[212:215], v[6:9]
	v_mfma_f32_16x16x32_bf16 v[2:5], v[174:177], v[212:215], v[2:5]
	s_setprio 0
	s_barrier
	s_cmp_ge_i32 s60, s57
	s_mov_b64 s[46:47], s[48:49]
	s_mov_b32 s50, s60
	s_cbranch_scc0 .LBB0_450

; __device__ __forceinline__ float bflo_(unsigned w) { return __uint_as_float(w << 16); }
; __device__ __forceinline__ float bfhi_(unsigned w) { return __uint_as_float(w & 0xffff0000u); }
; __device__ __forceinline__ unsigned cvt_pk_bf16(float lo, float hi) { unsigned r; asm volatile("v_cvt_pk_bf16_f32 %0, %1, %2" : "=v"(r) : "v"(lo), "v"(hi)); return r; }
; #define PG8_OPQ(p) asm volatile("" : "+v"(p))
;     __device__ __forceinline__ void operator()(const f32x4 (&acc)[2][2][4][2], const Unit& u, int wr, int wc, int fr, int fq) const {
;         char* p = (char*)(HB + (size_t)(wr * 64 + fr) * ldc + u.pn * BM + wc * 32 + 8 * fq);
;         const size_t step = (size_t)16 * ldc * 2;
; #pragma unroll
;         for (int ai = 0; ai < 2; ++ai) {
;             PG8_OPQ(p);
;             u32x4 h[4][2];
; #pragma unroll
;             for (int m = 0; m < 4; ++m)
; #pragma unroll
;                 for (int bj = 0; bj < 2; ++bj) h[m][bj] = *(const u32x4*)(p + m * step + bj * HALF * 2);
; #pragma unroll
;             for (int m = 0; m < 4; ++m)
; #pragma unroll
;                 for (int bj = 0; bj < 2; ++bj) { const f32x4 v0 = acc[ai][bj][m][0], v1 = acc[ai][bj][m][1]; const u32x4 hh = h[m][bj];
;                     u32x4 w;
;                     w.x = cvt_pk_bf16(bflo_(hh.x) * alpha + v0[0], bfhi_(hh.x) * alpha + v0[1]); w.y = cvt_pk_bf16(bflo_(hh.y) * alpha + v0[2], bfhi_(hh.y) * alpha + v0[3]);
;                     w.z = cvt_pk_bf16(bflo_(hh.z) * alpha + v1[0], bfhi_(hh.z) * alpha + v1[1]); w.w = cvt_pk_bf16(bflo_(hh.w) * alpha + v1[2], bfhi_(hh.w) * alpha + v1[3]);
;                     *(u32x4*)(p + m * step + bj * HALF * 2) = w; }
.LBB0_453:
	s_lshl_b32 s36, s8, 21
	v_lshl_add_u64 v[154:155], s[36:37], 1, v[148:149]
	flat_load_dwordx4 v[162:165], v[154:155]
	flat_load_dwordx4 v[166:169], v[154:155] offset:256
	v_add_co_u32_e32 v182, vcc, 0x8000, v154
	s_cmp_eq_u32 s8, 3
	s_nop 0
	v_addc_co_u32_e32 v183, vcc, 0, v155, vcc
	flat_load_dwordx4 v[170:173], v[182:183]
	flat_load_dwordx4 v[174:177], v[182:183] offset:256
	v_add_co_u32_e32 v158, vcc, 0x10000, v154
	s_mov_b64 s[8:9], -1
	s_nop 0
	v_addc_co_u32_e32 v159, vcc, 0, v155, vcc
	flat_load_dwordx4 v[178:181], v[158:159]
	flat_load_dwordx4 v[138:141], v[158:159] offset:256
	v_add_co_u32_e32 v156, vcc, 0x18000, v154
	s_waitcnt vmcnt(0) lgkmcnt(0)
	v_lshlrev_b32_e32 v184, 16, v162
	v_addc_co_u32_e32 v157, vcc, 0, v155, vcc
	flat_load_dwordx4 v[134:137], v[156:157]
	flat_load_dwordx4 v[130:133], v[156:157] offset:256
	v_and_b32_e32 v162, 0xffff0000, v162
	v_lshlrev_b32_e32 v185, 16, v163
	v_and_b32_e32 v163, 0xffff0000, v163
	v_lshlrev_b32_e32 v186, 16, v164
	v_and_b32_e32 v164, 0xffff0000, v164
	v_lshlrev_b32_e32 v187, 16, v165
	v_and_b32_e32 v165, 0xffff0000, v165
	v_fmac_f32_e32 v122, 0x3fb504f3, v184
	v_fmac_f32_e32 v123, 0x3fb504f3, v162
	v_fmac_f32_e32 v124, 0x3fb504f3, v185
	v_fmac_f32_e32 v125, 0x3fb504f3, v163
	v_fmac_f32_e32 v126, 0x3fb504f3, v186
	v_fmac_f32_e32 v127, 0x3fb504f3, v164
	v_fmac_f32_e32 v128, 0x3fb504f3, v187
	v_lshlrev_b32_e32 v188, 16, v166
	v_and_b32_e32 v166, 0xffff0000, v166
	v_lshlrev_b32_e32 v190, 16, v167
	v_and_b32_e32 v167, 0xffff0000, v167
	v_fmac_f32_e32 v129, 0x3fb504f3, v165
	v_cvt_pk_bf16_f32 v122, v122, v123
	v_cvt_pk_bf16_f32 v123, v124, v125
	v_cvt_pk_bf16_f32 v124, v126, v127
	v_cvt_pk_bf16_f32 v125, v128, v129
	v_lshlrev_b32_e32 v126, 16, v170
	v_and_b32_e32 v127, 0xffff0000, v170
	v_lshlrev_b32_e32 v128, 16, v171
	v_lshlrev_b32_e32 v162, 16, v172
	v_lshlrev_b32_e32 v192, 16, v168
	v_and_b32_e32 v168, 0xffff0000, v168
	v_lshlrev_b32_e32 v193, 16, v169
	v_and_b32_e32 v169, 0xffff0000, v169
	v_fmac_f32_e32 v118, 0x3fb504f3, v188
	v_fmac_f32_e32 v119, 0x3fb504f3, v166
	v_fmac_f32_e32 v120, 0x3fb504f3, v190
	v_fmac_f32_e32 v121, 0x3fb504f3, v167
	v_and_b32_e32 v129, 0xffff0000, v171
	v_and_b32_e32 v163, 0xffff0000, v172
	v_fmac_f32_e32 v110, 0x3fb504f3, v126
	v_fmac_f32_e32 v111, 0x3fb504f3, v127
	v_fmac_f32_e32 v112, 0x3fb504f3, v128
	v_fmac_f32_e32 v106, 0x3fb504f3, v162
	v_fmac_f32_e32 v114, 0x3fb504f3, v192
	v_fmac_f32_e32 v115, 0x3fb504f3, v168
	v_fmac_f32_e32 v116, 0x3fb504f3, v193
	v_fmac_f32_e32 v117, 0x3fb504f3, v169
	flat_store_dwordx4 v[154:155], v[122:125]
	v_cvt_pk_bf16_f32 v118, v118, v119
	v_cvt_pk_bf16_f32 v119, v120, v121
	v_cvt_pk_bf16_f32 v120, v114, v115
	v_cvt_pk_bf16_f32 v121, v116, v117
	v_fmac_f32_e32 v113, 0x3fb504f3, v129
	v_fmac_f32_e32 v107, 0x3fb504f3, v163
	flat_store_dwordx4 v[154:155], v[118:121] offset:256
	v_cvt_pk_bf16_f32 v110, v110, v111
	v_cvt_pk_bf16_f32 v111, v112, v113
	v_cvt_pk_bf16_f32 v112, v106, v107
	v_lshlrev_b32_e32 v106, 16, v174
	v_fmac_f32_e32 v102, 0x3fb504f3, v106
	v_and_b32_e32 v106, 0xffff0000, v174
	v_lshlrev_b32_e32 v164, 16, v173
	v_and_b32_e32 v165, 0xffff0000, v173
	v_fmac_f32_e32 v103, 0x3fb504f3, v106
	v_fmac_f32_e32 v108, 0x3fb504f3, v164
	v_fmac_f32_e32 v109, 0x3fb504f3, v165
	v_cvt_pk_bf16_f32 v113, v108, v109
	flat_store_dwordx4 v[182:183], v[110:113]
	v_cvt_pk_bf16_f32 v102, v102, v103
	v_lshlrev_b32_e32 v103, 16, v175
	v_fmac_f32_e32 v104, 0x3fb504f3, v103
	v_and_b32_e32 v103, 0xffff0000, v175
	v_fmac_f32_e32 v105, 0x3fb504f3, v103
	v_cvt_pk_bf16_f32 v103, v104, v105
	v_lshlrev_b32_e32 v104, 16, v176
	v_fmac_f32_e32 v98, 0x3fb504f3, v104
	v_and_b32_e32 v104, 0xffff0000, v176
	v_fmac_f32_e32 v99, 0x3fb504f3, v104
	v_cvt_pk_bf16_f32 v104, v98, v99
	v_lshlrev_b32_e32 v98, 16, v177
	v_fmac_f32_e32 v100, 0x3fb504f3, v98
	v_and_b32_e32 v98, 0xffff0000, v177
	v_fmac_f32_e32 v101, 0x3fb504f3, v98
	v_lshlrev_b32_e32 v98, 16, v178
	v_fmac_f32_e32 v94, 0x3fb504f3, v98
	v_and_b32_e32 v98, 0xffff0000, v178
	v_fmac_f32_e32 v95, 0x3fb504f3, v98
	v_cvt_pk_bf16_f32 v105, v100, v101
	flat_store_dwordx4 v[182:183], v[102:105] offset:256
	v_cvt_pk_bf16_f32 v94, v94, v95
	v_lshlrev_b32_e32 v95, 16, v179
	v_fmac_f32_e32 v96, 0x3fb504f3, v95
	v_and_b32_e32 v95, 0xffff0000, v179
	v_fmac_f32_e32 v97, 0x3fb504f3, v95
	v_cvt_pk_bf16_f32 v95, v96, v97
	v_lshlrev_b32_e32 v96, 16, v180
	v_fmac_f32_e32 v90, 0x3fb504f3, v96
	v_and_b32_e32 v96, 0xffff0000, v180
	v_fmac_f32_e32 v91, 0x3fb504f3, v96
	v_cvt_pk_bf16_f32 v96, v90, v91
	v_lshlrev_b32_e32 v90, 16, v181
	v_fmac_f32_e32 v92, 0x3fb504f3, v90
	v_and_b32_e32 v90, 0xffff0000, v181
	v_fmac_f32_e32 v93, 0x3fb504f3, v90
	v_lshlrev_b32_e32 v90, 16, v138
	v_fmac_f32_e32 v86, 0x3fb504f3, v90
	v_and_b32_e32 v90, 0xffff0000, v138
	v_fmac_f32_e32 v87, 0x3fb504f3, v90
	v_cvt_pk_bf16_f32 v97, v92, v93
	flat_store_dwordx4 v[158:159], v[94:97]
	v_cvt_pk_bf16_f32 v86, v86, v87
	v_lshlrev_b32_e32 v87, 16, v139
	v_fmac_f32_e32 v88, 0x3fb504f3, v87
	v_and_b32_e32 v87, 0xffff0000, v139
	v_fmac_f32_e32 v89, 0x3fb504f3, v87
	v_cvt_pk_bf16_f32 v87, v88, v89
	v_lshlrev_b32_e32 v88, 16, v140
	v_fmac_f32_e32 v82, 0x3fb504f3, v88
	v_and_b32_e32 v88, 0xffff0000, v140
	v_fmac_f32_e32 v83, 0x3fb504f3, v88
	v_cvt_pk_bf16_f32 v88, v82, v83
	v_lshlrev_b32_e32 v82, 16, v141
	v_fmac_f32_e32 v84, 0x3fb504f3, v82
	v_and_b32_e32 v82, 0xffff0000, v141
	v_fmac_f32_e32 v85, 0x3fb504f3, v82
	s_waitcnt vmcnt(0) lgkmcnt(0)
; __device__ __forceinline__ float bflo_(unsigned w) { return __uint_as_float(w << 16); }
; __device__ __forceinline__ float bfhi_(unsigned w) { return __uint_as_float(w & 0xffff0000u); }
; __device__ __forceinline__ unsigned cvt_pk_bf16(float lo, float hi) { unsigned r; asm volatile("v_cvt_pk_bf16_f32 %0, %1, %2" : "=v"(r) : "v"(lo), "v"(hi)); return r; }
; #define PG8_OPQ(p) asm volatile("" : "+v"(p))
;     __device__ __forceinline__ void operator()(const f32x4 (&acc)[2][2][4][2], const Unit& u, int wr, int wc, int fr, int fq) const {
;     ...
;         for (int ai = 0; ai < 2; ++ai) {
;             PG8_OPQ(p);
;             u32x4 h[4][2];
; #pragma unroll
;             for (int m = 0; m < 4; ++m)
; #pragma unroll
;                 for (int bj = 0; bj < 2; ++bj) h[m][bj] = *(const u32x4*)(p + m * step + bj * HALF * 2);
; #pragma unroll
;             for (int m = 0; m < 4; ++m)
; #pragma unroll
;                 for (int bj = 0; bj < 2; ++bj) { const f32x4 v0 = acc[ai][bj][m][0], v1 = acc[ai][bj][m][1]; const u32x4 hh = h[m][bj];
;                     u32x4 w;
;                     w.x = cvt_pk_bf16(bflo_(hh.x) * alpha + v0[0], bfhi_(hh.x) * alpha + v0[1]); w.y = cvt_pk_bf16(bflo_(hh.y) * alpha + v0[2], bfhi_(hh.y) * alpha + v0[3]);
;                     w.z = cvt_pk_bf16(bflo_(hh.z) * alpha + v1[0], bfhi_(hh.z) * alpha + v1[1]); w.w = cvt_pk_bf16(bflo_(hh.w) * alpha + v1[2], bfhi_(hh.w) * alpha + v1[3]);
;                     *(u32x4*)(p + m * step + bj * HALF * 2) = w; }
	v_lshlrev_b32_e32 v82, 16, v134
	v_fmac_f32_e32 v78, 0x3fb504f3, v82
	v_and_b32_e32 v82, 0xffff0000, v134
	v_fmac_f32_e32 v79, 0x3fb504f3, v82
	v_cvt_pk_bf16_f32 v89, v84, v85
	flat_store_dwordx4 v[158:159], v[86:89] offset:256
	v_cvt_pk_bf16_f32 v78, v78, v79
	v_lshlrev_b32_e32 v79, 16, v135
	v_fmac_f32_e32 v80, 0x3fb504f3, v79
	v_and_b32_e32 v79, 0xffff0000, v135
	v_fmac_f32_e32 v81, 0x3fb504f3, v79
	v_cvt_pk_bf16_f32 v79, v80, v81
	v_lshlrev_b32_e32 v80, 16, v136
	v_fmac_f32_e32 v74, 0x3fb504f3, v80
	v_and_b32_e32 v80, 0xffff0000, v136
	v_fmac_f32_e32 v75, 0x3fb504f3, v80
	v_cvt_pk_bf16_f32 v80, v74, v75
	v_lshlrev_b32_e32 v74, 16, v137
	v_fmac_f32_e32 v76, 0x3fb504f3, v74
	v_and_b32_e32 v74, 0xffff0000, v137
	v_fmac_f32_e32 v77, 0x3fb504f3, v74
	v_lshlrev_b32_e32 v74, 16, v130
	v_fmac_f32_e32 v70, 0x3fb504f3, v74
	v_and_b32_e32 v74, 0xffff0000, v130
	v_fmac_f32_e32 v71, 0x3fb504f3, v74
	v_cvt_pk_bf16_f32 v81, v76, v77
	flat_store_dwordx4 v[156:157], v[78:81]
	v_cvt_pk_bf16_f32 v70, v70, v71
	v_lshlrev_b32_e32 v71, 16, v131
	v_fmac_f32_e32 v72, 0x3fb504f3, v71
	v_and_b32_e32 v71, 0xffff0000, v131
	v_fmac_f32_e32 v73, 0x3fb504f3, v71
	v_cvt_pk_bf16_f32 v71, v72, v73
	v_lshlrev_b32_e32 v72, 16, v132
	v_fmac_f32_e32 v66, 0x3fb504f3, v72
	v_and_b32_e32 v72, 0xffff0000, v132
	v_fmac_f32_e32 v67, 0x3fb504f3, v72
	v_cvt_pk_bf16_f32 v72, v66, v67
	v_lshlrev_b32_e32 v66, 16, v133
	v_fmac_f32_e32 v68, 0x3fb504f3, v66
	v_and_b32_e32 v66, 0xffff0000, v133
	v_lshl_add_u64 v[100:101], v[154:155], 0, s[24:25]
	v_fmac_f32_e32 v69, 0x3fb504f3, v66
	v_cvt_pk_bf16_f32 v73, v68, v69
	flat_store_dwordx4 v[156:157], v[70:73] offset:256
	flat_load_dwordx4 v[72:75], v[100:101]
	flat_load_dwordx4 v[76:79], v[100:101] offset:256
	v_add_co_u32_e32 v102, vcc, s87, v100
	s_waitcnt vmcnt(0) lgkmcnt(0)
	v_lshlrev_b32_e32 v106, 16, v72
	v_addc_co_u32_e32 v103, vcc, 0, v101, vcc
	flat_load_dwordx4 v[80:83], v[102:103]
	flat_load_dwordx4 v[84:87], v[102:103] offset:256
	v_add_co_u32_e32 v104, vcc, s91, v100
	v_and_b32_e32 v72, 0xffff0000, v72
	s_nop 0
	v_addc_co_u32_e32 v105, vcc, 0, v101, vcc
	flat_load_dwordx4 v[88:91], v[104:105]
	flat_load_dwordx4 v[92:95], v[104:105] offset:256
	v_add_co_u32_e32 v70, vcc, s86, v100
	v_fmac_f32_e32 v62, 0x3fb504f3, v106
	s_nop 0
	v_addc_co_u32_e32 v71, vcc, 0, v101, vcc
	flat_load_dwordx4 v[96:99], v[70:71]
	flat_load_dwordx4 v[66:69], v[70:71] offset:256
	v_fmac_f32_e32 v63, 0x3fb504f3, v72
	v_cvt_pk_bf16_f32 v62, v62, v63
	v_lshlrev_b32_e32 v63, 16, v73
	v_fmac_f32_e32 v64, 0x3fb504f3, v63
	v_and_b32_e32 v63, 0xffff0000, v73
	v_fmac_f32_e32 v65, 0x3fb504f3, v63
	v_cvt_pk_bf16_f32 v63, v64, v65
	v_lshlrev_b32_e32 v64, 16, v74
	v_fmac_f32_e32 v58, 0x3fb504f3, v64
	v_and_b32_e32 v64, 0xffff0000, v74
	v_fmac_f32_e32 v59, 0x3fb504f3, v64
	v_cvt_pk_bf16_f32 v64, v58, v59
	v_lshlrev_b32_e32 v58, 16, v75
	v_fmac_f32_e32 v60, 0x3fb504f3, v58
	v_and_b32_e32 v58, 0xffff0000, v75
	v_fmac_f32_e32 v61, 0x3fb504f3, v58
	v_lshlrev_b32_e32 v58, 16, v76
	v_fmac_f32_e32 v54, 0x3fb504f3, v58
	v_and_b32_e32 v58, 0xffff0000, v76
	v_fmac_f32_e32 v55, 0x3fb504f3, v58
	v_cvt_pk_bf16_f32 v65, v60, v61
	flat_store_dwordx4 v[100:101], v[62:65]
	v_cvt_pk_bf16_f32 v54, v54, v55
	v_lshlrev_b32_e32 v55, 16, v77
	v_fmac_f32_e32 v56, 0x3fb504f3, v55
	v_and_b32_e32 v55, 0xffff0000, v77
	v_fmac_f32_e32 v57, 0x3fb504f3, v55
	v_cvt_pk_bf16_f32 v55, v56, v57
	v_lshlrev_b32_e32 v56, 16, v78
	v_fmac_f32_e32 v50, 0x3fb504f3, v56
	v_and_b32_e32 v56, 0xffff0000, v78
	v_fmac_f32_e32 v51, 0x3fb504f3, v56
	v_cvt_pk_bf16_f32 v56, v50, v51
	v_lshlrev_b32_e32 v50, 16, v79
	v_fmac_f32_e32 v52, 0x3fb504f3, v50
	v_and_b32_e32 v50, 0xffff0000, v79
	v_fmac_f32_e32 v53, 0x3fb504f3, v50
	v_cvt_pk_bf16_f32 v57, v52, v53
	flat_store_dwordx4 v[100:101], v[54:57] offset:256
	s_waitcnt vmcnt(0) lgkmcnt(0)
; __device__ __forceinline__ float bflo_(unsigned w) { return __uint_as_float(w << 16); }
; __device__ __forceinline__ float bfhi_(unsigned w) { return __uint_as_float(w & 0xffff0000u); }
; __device__ __forceinline__ unsigned cvt_pk_bf16(float lo, float hi) { unsigned r; asm volatile("v_cvt_pk_bf16_f32 %0, %1, %2" : "=v"(r) : "v"(lo), "v"(hi)); return r; }
; #define PG8_WAIT_V(n) asm volatile("s_waitcnt vmcnt(" #n ")" ::: "memory")
; #define PG8_BAR __builtin_amdgcn_s_barrier()
; template <class Epi, class Sched>
; __device__ __forceinline__ void gemm_phase(LAS unsigned char* lds, const Gemm g, const Sched& S, const Epi& E) {
;     ...
;     PG8_WAIT_V(0);
;     PG8_BAR;
;     __device__ __forceinline__ void operator()(const f32x4 (&acc)[2][2][4][2], const Unit& u, int wr, int wc, int fr, int fq) const {
;     ...
;             for (int m = 0; m < 4; ++m)
; #pragma unroll
;                 for (int bj = 0; bj < 2; ++bj) { const f32x4 v0 = acc[ai][bj][m][0], v1 = acc[ai][bj][m][1]; const u32x4 hh = h[m][bj];
;                     u32x4 w;
;                     w.x = cvt_pk_bf16(bflo_(hh.x) * alpha + v0[0], bfhi_(hh.x) * alpha + v0[1]); w.y = cvt_pk_bf16(bflo_(hh.y) * alpha + v0[2], bfhi_(hh.y) * alpha + v0[3]);
;                     w.z = cvt_pk_bf16(bflo_(hh.z) * alpha + v1[0], bfhi_(hh.z) * alpha + v1[1]); w.w = cvt_pk_bf16(bflo_(hh.w) * alpha + v1[2], bfhi_(hh.w) * alpha + v1[3]);
;                     *(u32x4*)(p + m * step + bj * HALF * 2) = w; }
;             p += 8 * step;
	v_lshlrev_b32_e32 v50, 16, v80
	v_fmac_f32_e32 v46, 0x3fb504f3, v50
	v_and_b32_e32 v50, 0xffff0000, v80
	v_fmac_f32_e32 v47, 0x3fb504f3, v50
	v_cvt_pk_bf16_f32 v46, v46, v47
	v_lshlrev_b32_e32 v47, 16, v81
	v_fmac_f32_e32 v48, 0x3fb504f3, v47
	v_and_b32_e32 v47, 0xffff0000, v81
	v_fmac_f32_e32 v49, 0x3fb504f3, v47
	v_cvt_pk_bf16_f32 v47, v48, v49
	v_lshlrev_b32_e32 v48, 16, v82
	v_fmac_f32_e32 v42, 0x3fb504f3, v48
	v_and_b32_e32 v48, 0xffff0000, v82
	v_fmac_f32_e32 v43, 0x3fb504f3, v48
	v_cvt_pk_bf16_f32 v48, v42, v43
	v_lshlrev_b32_e32 v42, 16, v83
	v_fmac_f32_e32 v44, 0x3fb504f3, v42
	v_and_b32_e32 v42, 0xffff0000, v83
	v_fmac_f32_e32 v45, 0x3fb504f3, v42
	v_lshlrev_b32_e32 v42, 16, v84
	v_fmac_f32_e32 v38, 0x3fb504f3, v42
	v_and_b32_e32 v42, 0xffff0000, v84
	v_fmac_f32_e32 v39, 0x3fb504f3, v42
	v_cvt_pk_bf16_f32 v49, v44, v45
	flat_store_dwordx4 v[102:103], v[46:49]
	v_cvt_pk_bf16_f32 v38, v38, v39
	v_lshlrev_b32_e32 v39, 16, v85
	v_fmac_f32_e32 v40, 0x3fb504f3, v39
	v_and_b32_e32 v39, 0xffff0000, v85
	v_fmac_f32_e32 v41, 0x3fb504f3, v39
	v_cvt_pk_bf16_f32 v39, v40, v41
	v_lshlrev_b32_e32 v40, 16, v86
	v_fmac_f32_e32 v34, 0x3fb504f3, v40
	v_and_b32_e32 v40, 0xffff0000, v86
	v_fmac_f32_e32 v35, 0x3fb504f3, v40
	v_cvt_pk_bf16_f32 v40, v34, v35
	v_lshlrev_b32_e32 v34, 16, v87
	v_fmac_f32_e32 v36, 0x3fb504f3, v34
	v_and_b32_e32 v34, 0xffff0000, v87
	v_fmac_f32_e32 v37, 0x3fb504f3, v34
	v_lshlrev_b32_e32 v34, 16, v88
	v_fmac_f32_e32 v30, 0x3fb504f3, v34
	v_and_b32_e32 v34, 0xffff0000, v88
	v_fmac_f32_e32 v31, 0x3fb504f3, v34
	v_cvt_pk_bf16_f32 v41, v36, v37
	flat_store_dwordx4 v[102:103], v[38:41] offset:256
	v_cvt_pk_bf16_f32 v30, v30, v31
	v_lshlrev_b32_e32 v31, 16, v89
	v_fmac_f32_e32 v32, 0x3fb504f3, v31
	v_and_b32_e32 v31, 0xffff0000, v89
	v_fmac_f32_e32 v33, 0x3fb504f3, v31
	v_cvt_pk_bf16_f32 v31, v32, v33
	v_lshlrev_b32_e32 v32, 16, v90
	v_fmac_f32_e32 v26, 0x3fb504f3, v32
	v_and_b32_e32 v32, 0xffff0000, v90
	v_fmac_f32_e32 v27, 0x3fb504f3, v32
	v_cvt_pk_bf16_f32 v32, v26, v27
	v_lshlrev_b32_e32 v26, 16, v91
	v_fmac_f32_e32 v28, 0x3fb504f3, v26
	v_and_b32_e32 v26, 0xffff0000, v91
	v_fmac_f32_e32 v29, 0x3fb504f3, v26
	v_lshlrev_b32_e32 v26, 16, v92
	v_fmac_f32_e32 v22, 0x3fb504f3, v26
	v_and_b32_e32 v26, 0xffff0000, v92
	v_fmac_f32_e32 v23, 0x3fb504f3, v26
	v_cvt_pk_bf16_f32 v33, v28, v29
	flat_store_dwordx4 v[104:105], v[30:33]
	v_cvt_pk_bf16_f32 v22, v22, v23
	v_lshlrev_b32_e32 v23, 16, v93
	v_fmac_f32_e32 v24, 0x3fb504f3, v23
	v_and_b32_e32 v23, 0xffff0000, v93
	v_fmac_f32_e32 v25, 0x3fb504f3, v23
	v_cvt_pk_bf16_f32 v23, v24, v25
	v_lshlrev_b32_e32 v24, 16, v94
	v_fmac_f32_e32 v18, 0x3fb504f3, v24
	v_and_b32_e32 v24, 0xffff0000, v94
	v_fmac_f32_e32 v19, 0x3fb504f3, v24
	v_cvt_pk_bf16_f32 v24, v18, v19
	v_lshlrev_b32_e32 v18, 16, v95
	v_fmac_f32_e32 v20, 0x3fb504f3, v18
	v_and_b32_e32 v18, 0xffff0000, v95
	v_fmac_f32_e32 v21, 0x3fb504f3, v18
	v_lshlrev_b32_e32 v18, 16, v96
	v_fmac_f32_e32 v14, 0x3fb504f3, v18
	v_and_b32_e32 v18, 0xffff0000, v96
	v_fmac_f32_e32 v15, 0x3fb504f3, v18
	v_cvt_pk_bf16_f32 v25, v20, v21
	flat_store_dwordx4 v[104:105], v[22:25] offset:256
	v_cvt_pk_bf16_f32 v14, v14, v15
	v_lshlrev_b32_e32 v15, 16, v97
	v_fmac_f32_e32 v16, 0x3fb504f3, v15
	v_and_b32_e32 v15, 0xffff0000, v97
	v_fmac_f32_e32 v17, 0x3fb504f3, v15
	v_cvt_pk_bf16_f32 v15, v16, v17
	v_lshlrev_b32_e32 v16, 16, v98
	v_fmac_f32_e32 v10, 0x3fb504f3, v16
	v_and_b32_e32 v16, 0xffff0000, v98
	v_fmac_f32_e32 v11, 0x3fb504f3, v16
	v_cvt_pk_bf16_f32 v16, v10, v11
	v_lshlrev_b32_e32 v10, 16, v99
	v_fmac_f32_e32 v12, 0x3fb504f3, v10
	v_and_b32_e32 v10, 0xffff0000, v99
	v_fmac_f32_e32 v13, 0x3fb504f3, v10
	v_lshlrev_b32_e32 v10, 16, v66
	v_fmac_f32_e32 v6, 0x3fb504f3, v10
	v_and_b32_e32 v10, 0xffff0000, v66
	v_fmac_f32_e32 v7, 0x3fb504f3, v10
	v_cvt_pk_bf16_f32 v17, v12, v13
	flat_store_dwordx4 v[70:71], v[14:17]
	v_cvt_pk_bf16_f32 v6, v6, v7
	v_lshlrev_b32_e32 v7, 16, v67
	v_fmac_f32_e32 v8, 0x3fb504f3, v7
	v_and_b32_e32 v7, 0xffff0000, v67
	v_fmac_f32_e32 v9, 0x3fb504f3, v7
	v_cvt_pk_bf16_f32 v7, v8, v9
	v_lshlrev_b32_e32 v8, 16, v68
	v_fmac_f32_e32 v2, 0x3fb504f3, v8
	v_and_b32_e32 v8, 0xffff0000, v68
	v_fmac_f32_e32 v3, 0x3fb504f3, v8
	v_cvt_pk_bf16_f32 v8, v2, v3
	v_lshlrev_b32_e32 v2, 16, v69
	v_fmac_f32_e32 v4, 0x3fb504f3, v2
	v_and_b32_e32 v2, 0xffff0000, v69
	v_fmac_f32_e32 v5, 0x3fb504f3, v2
	v_cvt_pk_bf16_f32 v9, v4, v5
	flat_store_dwordx4 v[70:71], v[6:9] offset:256
	s_cbranch_scc1 .LBB0_445
	s_andn2_b64 vcc, exec, s[26:27]
	s_cbranch_vccnz .LBB0_444
	s_barrier
	s_branch .LBB0_444
.LBB0_456:
	v_readlane_b32 s2, v249, 0
	v_readlane_b32 s3, v249, 1
	s_waitcnt vmcnt(0)
	s_barrier
	s_waitcnt lgkmcnt(0)
	s_barrier
	v_readfirstlane_b32 s98, v189
	s_nop 3
	s_cmp_ge_u32 s98, 64
	s_cbranch_scc1 .Lgrp_bar2_done
	s_lshr_b32 s98, s88, 21
	s_and_b32 s99, s98, 7
	s_lshr_b32 s98, s98, 5
	s_lshl_b32 s98, s98, 3
	s_or_b32 s98, s98, s99
	s_lshl_b32 s98, s98, 4
	v_readlane_b32 s99, v248, 36
	s_nop 3
	s_lshl_b32 s99, s99, 3
	s_add_u32 s98, s98, s99
	s_add_u32 s98, s98, 14340
	v_mov_b32_e32 v2, s98
	v_mov_b32_e32 v3, 1
	s_mov_b64 s[100:101], exec
	s_mov_b64 exec, 1
	buffer_wbl2 sc1
	s_waitcnt vmcnt(0)
	global_atomic_add v2, v3, s[80:81]
	s_mov_b32 s99, 0

; __device__ __forceinline__ void ln_panel_b(bf16_t* hb, float* outf, const float* gam, const float* bet) {
;     int tid_ = threadIdx.x; asm volatile("" : "+v"(tid_));
;     const int lane = tid_ & 63, wave = __builtin_amdgcn_readfirstlane(tid_ >> 6);
;     constexpr int NB = 2;
;     u32x4 nxt[NB][2];
;     const int r0 = wave * 32;
; #pragma unroll
;     for (int b = 0; b < NB; ++b)
; #pragma unroll
;         for (int j = 0; j < 2; ++j) nxt[b][j] = ((const u32x4*)(hb + (size_t)(r0 + b) * DM))[lane + 64 * j];
;     f32x4 gv[2][2], bv[2][2];
; #pragma unroll
;     for (int j = 0; j < 2; ++j)
; #pragma unroll
;         for (int q = 0; q < 2; ++q) { gv[j][q] = *(const f32x4*)(gam + 512 * j + 8 * lane + 4 * q); bv[j][q] = *(const f32x4*)(bet + 512 * j + 8 * lane + 4 * q); }
.Lgrp_bar2_done:
	s_barrier
	s_load_dwordx8 s[40:47], s[2:3], 0xe0
	v_readlane_b32 s2, v249, 8
	v_readlane_b32 s3, v249, 9
	v_mov_b32_e32 v0, v189
	s_waitcnt lgkmcnt(0)
	s_add_u32 s1, s46, s2
	s_addc_u32 s2, s47, s3
	s_add_u32 s4, s1, 0x6000000
	s_addc_u32 s5, s2, 0
	v_readlane_b32 s2, v249, 4
	v_readlane_b32 s3, v249, 5
	s_lshl_b64 s[2:3], s[2:3], 2
	s_add_u32 s1, s44, s2
	s_addc_u32 s8, s45, s3
	v_readlane_b32 s2, v248, 32
	v_readlane_b32 s3, v248, 33
	s_and_b64 s[2:3], s[2:3], exec
	s_cselect_b32 s11, s8, 0
	s_cselect_b32 s10, s1, 0
	s_add_u32 s2, s40, s20
	s_addc_u32 s3, s41, s21
	s_add_u32 s8, s42, s20
	v_readfirstlane_b32 s1, v0
	s_addc_u32 s9, s43, s21
	s_ashr_i32 s36, s1, 1
	s_and_b32 s18, s36, 0xffffffe0
	s_ashr_i32 s19, s18, 31
	s_lshl_b64 s[38:39], s[18:19], 11
	v_and_b32_e32 v66, 63, v0
	s_add_u32 s20, s4, s38
	s_addc_u32 s21, s5, s39
	v_lshlrev_b32_e32 v0, 4, v66
	global_load_dwordx4 v[50:53], v0, s[20:21]
	global_load_dwordx4 v[62:65], v0, s[20:21] offset:1024
	s_or_b32 s20, s18, 1
	s_ashr_i32 s21, s20, 31
	s_lshl_b64 s[20:21], s[20:21], 11
	s_add_u32 s20, s4, s20
	s_addc_u32 s21, s5, s21
	v_lshlrev_b32_e32 v34, 5, v66
	global_load_dwordx4 v[54:57], v0, s[20:21]
	global_load_dwordx4 v[58:61], v0, s[20:21] offset:1024
	global_load_dwordx4 v[26:29], v34, s[2:3]
	global_load_dwordx4 v[18:21], v34, s[2:3] offset:16
	global_load_dwordx4 v[30:33], v34, s[8:9]
	global_load_dwordx4 v[22:25], v34, s[8:9] offset:16
	global_load_dwordx4 v[10:13], v34, s[2:3] offset:2048
	global_load_dwordx4 v[2:5], v34, s[2:3] offset:2064
	global_load_dwordx4 v[14:17], v34, s[8:9] offset:2048
	global_load_dwordx4 v[6:9], v34, s[8:9] offset:2064
	s_cmp_lg_u64 s[10:11], 0
	v_readlane_b32 s2, v249, 6
	s_cselect_b64 s[26:27], -1, 0
	v_readlane_b32 s3, v249, 7
	s_add_u32 s1, s46, s2
	s_addc_u32 s3, s47, s3
	s_add_u32 s2, s1, s38
	s_addc_u32 s3, s3, s39
	v_lshl_add_u64 v[70:71], s[2:3], 0, v[0:1]
	s_lshl_b64 s[2:3], s[18:19], 12
	s_add_u32 s2, s10, s2
	v_mov_b32_e32 v35, v1
	s_addc_u32 s3, s11, s3
	v_lshl_add_u64 v[34:35], s[2:3], 0, v[34:35]
	s_mov_b64 s[2:3], 0x1000
	v_lshlrev_b32_e32 v68, 3, v66
	s_mov_b64 s[20:21], 0
	v_lshl_add_u64 v[72:73], v[34:35], 0, s[2:3]
	s_branch .LBB0_458
